# 5952 of the layer-1 FFN up-weight conversion tiles moved out of the first GEMM phase into the idle tail of the half-GLU GEMM phase (248 workgroups wait there for the 8 that run a second tile), done by
# speedup vs baseline: 1.0040x; 1.0010x over previous
.LBB0_342:
	v_readlane_b32 s6, v255, 9
	s_cmp_gt_i32 s6, 0x100bf
	v_readlane_b32 s7, v255, 10
	s_cbranch_scc1 .LBB0_444
	v_readlane_b32 s14, v255, 9
	s_cmpk_gt_u32 s14, 0x3ff
	v_readlane_b32 s15, v255, 10
	s_cbranch_scc1 .LBB0_345
	s_mov_b64 s[6:7], s[0:1]
	s_load_dwordx2 s[6:7], s[6:7], 0xa0
	s_lshl_b32 s3, s14, 1
	s_and_b32 s3, s3, 0x7c0
	s_lshl_b32 s8, s3, 13
	s_movk_i32 s15, 0x800
	s_waitcnt lgkmcnt(0)
	s_add_u32 s6, s6, s8
	s_addc_u32 s7, s7, 0
	s_lshl_b32 s8, s14, 6
	s_and_b32 s10, s8, 0x7c0
	s_lshl_b32 s8, s10, 2
	s_add_u32 s8, s6, s8
	s_addc_u32 s9, s7, 0
	s_lshl_b32 s6, s10, 12
	s_add_u32 s6, s38, s6
	s_addc_u32 s7, s39, 0
	s_lshl_b32 s3, s3, 1
	s_add_u32 s3, s6, s3
	s_addc_u32 s7, s7, 0
	s_add_u32 s6, s3, 0x2c00000
	s_addc_u32 s7, s7, 0
	s_add_i32 s3, s14, 0xfffffc00
	s_cmpk_gt_u32 s3, 0xfff
	s_cbranch_scc0 .LBB0_346
	s_branch .LBB0_347

.LBB0_357:
	v_and_b32_e32 v195, 48, v0
	v_mul_u32_u24_e32 v2, s15, v195
	v_mov_b32_e32 v197, 0
	v_lshlrev_b32_e32 v196, 2, v2
	v_and_b32_e32 v1, 60, v1
	v_lshl_add_u64 v[2:3], s[8:9], 0, v[196:197]
	v_lshlrev_b32_e32 v196, 2, v1
	s_mov_b32 s13, 0
	v_lshl_add_u64 v[10:11], v[2:3], 0, v[196:197]
	s_lshl_b32 s12, s15, 2
	v_lshl_add_u64 v[12:13], v[10:11], 0, s[12:13]
	v_lshl_add_u64 v[18:19], v[12:13], 0, s[12:13]
	v_lshl_add_u64 v[20:21], v[18:19], 0, s[12:13]
	v_lshl_add_u64 v[26:27], v[20:21], 0, s[12:13]
	v_lshl_add_u64 v[28:29], v[26:27], 0, s[12:13]
	v_lshl_add_u64 v[34:35], v[28:29], 0, s[12:13]
	v_lshl_add_u64 v[36:37], v[34:35], 0, s[12:13]
	v_lshl_add_u64 v[38:39], v[36:37], 0, s[12:13]
	v_lshl_add_u64 v[42:43], v[38:39], 0, s[12:13]
	v_lshl_add_u64 v[46:47], v[42:43], 0, s[12:13]
	v_lshl_add_u64 v[50:51], v[46:47], 0, s[12:13]
	v_lshl_add_u64 v[54:55], v[50:51], 0, s[12:13]
	v_lshl_add_u64 v[58:59], v[54:55], 0, s[12:13]
	v_lshl_add_u64 v[62:63], v[58:59], 0, s[12:13]
	global_load_dwordx4 v[2:5], v[10:11], off nt
	global_load_dwordx4 v[6:9], v[12:13], off nt
	s_nop 0
	global_load_dwordx4 v[10:13], v[18:19], off nt
	global_load_dwordx4 v[14:17], v[20:21], off nt
	s_nop 0
	global_load_dwordx4 v[18:21], v[26:27], off nt
	global_load_dwordx4 v[22:25], v[28:29], off nt
	s_nop 0
	global_load_dwordx4 v[26:29], v[34:35], off nt
	global_load_dwordx4 v[30:33], v[36:37], off nt
	v_readlane_b32 s8, v255, 11
	global_load_dwordx4 v[34:37], v[38:39], off nt
	v_readlane_b32 s10, v255, 9
	global_load_dwordx4 v[38:41], v[42:43], off nt
	v_readlane_b32 s9, v255, 12
	global_load_dwordx4 v[42:45], v[46:47], off nt
	s_mov_b32 s40, s23
	global_load_dwordx4 v[46:49], v[50:51], off nt
	v_readlane_b32 s11, v255, 10
	global_load_dwordx4 v[50:53], v[54:55], off nt
	s_nop 0
	global_load_dwordx4 v[54:57], v[58:59], off nt
	s_nop 0
	global_load_dwordx4 v[58:61], v[62:63], off nt
	v_lshl_add_u64 v[62:63], v[62:63], 0, s[12:13]
	global_load_dwordx4 v[62:65], v[62:63], off nt
	s_add_i32 s12, s8, s10
	s_cmp_lt_i32 s12, 0x100c0
	s_cselect_b64 s[14:15], -1, 0
	s_cmp_gt_i32 s12, 0x100bf
	s_mov_b64 s[8:9], s[6:7]
	s_cbranch_scc1 .LBB0_377
	s_mov_b64 s[10:11], 0
	s_cmpk_gt_u32 s12, 0x3ff
	s_mov_b64 s[8:9], 0
	s_cbranch_scc1 .LBB0_366
	s_mov_b64 s[8:9], s[0:1]
	s_load_dwordx2 s[8:9], s[8:9], 0xa0
	s_lshl_b32 s10, s12, 1
	s_and_b32 s13, s10, 0x7c0
	s_lshl_b32 s10, s13, 13
	s_waitcnt lgkmcnt(0)
	s_add_u32 s8, s8, s10
	s_addc_u32 s9, s9, 0
	s_lshl_b32 s10, s12, 6
	s_and_b32 s16, s10, 0x7c0
	s_lshl_b32 s10, s16, 2
	s_add_u32 s10, s8, s10
	s_addc_u32 s11, s9, 0
	s_lshl_b32 s8, s16, 12
	s_add_u32 s8, s38, s8
	s_addc_u32 s9, s39, 0
	s_lshl_b32 s13, s13, 1
	s_add_u32 s8, s8, s13
	s_addc_u32 s9, s9, 0
	s_add_u32 s8, s8, 0x2c00000
	s_addc_u32 s9, s9, 0
	s_movk_i32 s13, 0x800
	s_add_i32 s16, s12, 0xfffffc00
	s_cmpk_gt_u32 s16, 0xfff
	s_cbranch_scc0 .LBB0_367

.LBB0_380:
	s_add_i32 s42, s35, s24
	s_cmp_lt_i32 s42, 0x100c0
	s_cselect_b64 s[16:17], -1, 0
	s_cmp_gt_i32 s42, 0x100bf
	s_cbranch_scc1 .LBB0_396
	s_cmpk_gt_u32 s42, 0x3ff
	s_cbranch_scc1 .LBB0_383
	s_mov_b64 s[12:13], s[0:1]
	s_load_dwordx2 s[12:13], s[12:13], 0xa0
	s_lshl_b32 s10, s42, 1
	s_and_b32 s10, s10, 0x7c0
	s_lshl_b32 s18, s10, 13
	s_movk_i32 s46, 0x800
	s_waitcnt lgkmcnt(0)
	s_add_u32 s12, s12, s18
	s_addc_u32 s13, s13, 0
	s_lshl_b32 s18, s42, 6
	s_and_b32 s20, s18, 0x7c0
	s_lshl_b32 s18, s20, 2
	s_add_u32 s18, s12, s18
	s_addc_u32 s19, s13, 0
	s_lshl_b32 s12, s20, 12
	s_add_u32 s12, s25, s12
	s_addc_u32 s13, s26, 0
	s_lshl_b32 s10, s10, 1
	s_add_u32 s12, s12, s10
	s_addc_u32 s13, s13, 0
	s_add_i32 s10, s42, 0xfffffc00
	s_cmpk_gt_u32 s10, 0xfff
	s_cbranch_scc0 .LBB0_384
	s_branch .LBB0_385

.LBB0_396:
	s_waitcnt vmcnt(0)
	v_cvt_pk_bf16_f32 v218, v2, v6
	v_cvt_pk_bf16_f32 v219, v10, v14
	v_cvt_pk_bf16_f32 v220, v18, v22
	v_cvt_pk_bf16_f32 v221, v26, v30
	v_cvt_pk_bf16_f32 v222, v34, v38
	v_cvt_pk_bf16_f32 v223, v42, v46
	v_cvt_pk_bf16_f32 v224, v50, v54
	v_cvt_pk_bf16_f32 v225, v58, v62
	ds_write_b128 v1, v[218:221]
	ds_write_b128 v1, v[222:225] offset:16
	v_cvt_pk_bf16_f32 v218, v3, v7
	v_cvt_pk_bf16_f32 v219, v11, v15
	v_cvt_pk_bf16_f32 v220, v19, v23
	v_cvt_pk_bf16_f32 v221, v27, v31
	v_cvt_pk_bf16_f32 v222, v35, v39
	v_cvt_pk_bf16_f32 v223, v43, v47
	v_cvt_pk_bf16_f32 v224, v51, v55
	v_cvt_pk_bf16_f32 v225, v59, v63
	ds_write2_b64 v1, v[218:219], v[220:221] offset0:17 offset1:18
	ds_write2_b64 v1, v[222:223], v[224:225] offset0:19 offset1:20
	v_cvt_pk_bf16_f32 v218, v4, v8
	v_cvt_pk_bf16_f32 v219, v12, v16
	v_cvt_pk_bf16_f32 v220, v20, v24
	v_cvt_pk_bf16_f32 v221, v28, v32
	v_cvt_pk_bf16_f32 v222, v36, v40
	v_cvt_pk_bf16_f32 v223, v44, v48
	v_cvt_pk_bf16_f32 v224, v52, v56
	v_cvt_pk_bf16_f32 v225, v60, v64
	ds_write_b128 v1, v[218:221] offset:272
	ds_write_b128 v1, v[222:225] offset:288
	v_cvt_pk_bf16_f32 v218, v5, v9
	v_cvt_pk_bf16_f32 v219, v13, v17
	v_cvt_pk_bf16_f32 v220, v21, v25
	v_cvt_pk_bf16_f32 v221, v29, v33
	v_cvt_pk_bf16_f32 v222, v37, v41
	v_cvt_pk_bf16_f32 v223, v45, v49
	v_cvt_pk_bf16_f32 v224, v53, v57
	v_cvt_pk_bf16_f32 v225, v61, v65
	ds_write2_b64 v1, v[218:219], v[220:221] offset0:51 offset1:52
	ds_write2_b64 v1, v[222:223], v[224:225] offset0:53 offset1:54
	s_waitcnt lgkmcnt(0)
	v_lshlrev_b32_e32 v202, 1, v200
	ds_read2_b64 v[218:221], v199 offset1:1
	v_lshl_add_u64 v[226:227], s[6:7], 0, v[202:203]
	v_mad_u64_u32 v[222:223], s[18:19], s23, v198, 0
	v_lshl_add_u64 v[228:229], v[222:223], 1, v[226:227]
	ds_read2_b64 v[222:225], v199 offset0:136 offset1:137
	s_waitcnt lgkmcnt(1)
	global_store_dwordx4 v[228:229], v[218:221], off
	v_add_u32_e32 v201, 0x880, v199
	v_add_u32_e32 v205, 0xcc0, v199
	v_mad_u64_u32 v[218:219], s[18:19], s23, v204, 0
	v_lshl_add_u64 v[218:219], v[218:219], 1, v[226:227]
	s_waitcnt lgkmcnt(0)
	global_store_dwordx4 v[218:219], v[222:225], off
	ds_read2_b64 v[218:221], v201 offset1:1
	v_add_u32_e32 v207, 0x1100, v199
	v_mad_u64_u32 v[222:223], s[18:19], s23, v206, 0
	v_lshl_add_u64 v[228:229], v[222:223], 1, v[226:227]
	ds_read2_b64 v[222:225], v205 offset1:1
	s_waitcnt lgkmcnt(1)
	global_store_dwordx4 v[228:229], v[218:221], off
	v_add_u32_e32 v209, 0x1540, v199
	v_add_u32_e32 v211, 0x1980, v199
	v_mad_u64_u32 v[218:219], s[18:19], s23, v208, 0
	v_lshl_add_u64 v[218:219], v[218:219], 1, v[226:227]
	s_waitcnt lgkmcnt(0)
	global_store_dwordx4 v[218:219], v[222:225], off
	ds_read2_b64 v[218:221], v207 offset1:1
	v_add_u32_e32 v213, 0x1dc0, v199
	v_mad_u64_u32 v[222:223], s[18:19], s23, v210, 0
	v_lshl_add_u64 v[228:229], v[222:223], 1, v[226:227]
	ds_read2_b64 v[222:225], v209 offset1:1
	s_waitcnt lgkmcnt(1)
	global_store_dwordx4 v[228:229], v[218:221], off
	s_andn2_b64 vcc, exec, s[14:15]
	s_nop 0
	v_mad_u64_u32 v[218:219], s[18:19], s23, v212, 0
	v_lshl_add_u64 v[218:219], v[218:219], 1, v[226:227]
	s_waitcnt lgkmcnt(0)
	global_store_dwordx4 v[218:219], v[222:225], off
	ds_read2_b64 v[218:221], v211 offset1:1
	s_nop 0
	v_mad_u64_u32 v[222:223], s[18:19], s23, v214, 0
	v_lshl_add_u64 v[228:229], v[222:223], 1, v[226:227]
	ds_read2_b64 v[222:225], v213 offset1:1
	s_waitcnt lgkmcnt(1)
	global_store_dwordx4 v[228:229], v[218:221], off
	s_nop 1
	v_mad_u64_u32 v[218:219], s[18:19], s23, v216, 0
	v_lshl_add_u64 v[218:219], v[218:219], 1, v[226:227]
	s_waitcnt lgkmcnt(0)
	global_store_dwordx4 v[218:219], v[222:225], off
	s_waitcnt lgkmcnt(0)
	s_mov_b64 s[18:19], 0
	s_cbranch_vccnz .LBB0_378
	s_add_i32 s42, s35, s34
	s_cmp_gt_i32 s42, 0x100bf
	s_cselect_b64 s[18:19], -1, 0
	s_and_b64 vcc, exec, s[18:19]
	s_cbranch_vccnz .LBB0_417
	s_cmpk_gt_u32 s42, 0x3ff
	s_cbranch_scc1 .LBB0_404
	s_mov_b64 s[6:7], s[0:1]
	s_load_dwordx2 s[6:7], s[6:7], 0xa0
	s_lshl_b32 s10, s42, 1
	s_and_b32 s10, s10, 0x7c0
	s_lshl_b32 s14, s10, 13
	s_movk_i32 s46, 0x800
	s_waitcnt lgkmcnt(0)
	s_add_u32 s6, s6, s14
	s_addc_u32 s7, s7, 0
	s_lshl_b32 s14, s42, 6
	s_and_b32 s20, s14, 0x7c0
	s_lshl_b32 s14, s20, 2
	s_add_u32 s14, s6, s14
	s_addc_u32 s15, s7, 0
	s_lshl_b32 s6, s20, 12
	s_add_u32 s6, s25, s6
	s_addc_u32 s7, s26, 0
	s_lshl_b32 s10, s10, 1
	s_add_u32 s6, s6, s10
	s_addc_u32 s7, s7, 0
	s_add_i32 s10, s42, 0xfffffc00
	s_cmpk_gt_u32 s10, 0xfff
	s_cbranch_scc0 .LBB0_405
	s_branch .LBB0_406

.LBB0_417:
	v_cvt_pk_bf16_f32 v218, v66, v70
	v_cvt_pk_bf16_f32 v219, v74, v78
	v_cvt_pk_bf16_f32 v220, v82, v86
	v_cvt_pk_bf16_f32 v221, v90, v94
	v_cvt_pk_bf16_f32 v222, v98, v102
	v_cvt_pk_bf16_f32 v223, v106, v110
	v_cvt_pk_bf16_f32 v224, v114, v118
	v_cvt_pk_bf16_f32 v225, v122, v126
	ds_write_b128 v1, v[218:221]
	ds_write_b128 v1, v[222:225] offset:16
	v_cvt_pk_bf16_f32 v218, v67, v71
	v_cvt_pk_bf16_f32 v219, v75, v79
	v_cvt_pk_bf16_f32 v220, v83, v87
	v_cvt_pk_bf16_f32 v221, v91, v95
	v_cvt_pk_bf16_f32 v222, v99, v103
	v_cvt_pk_bf16_f32 v223, v107, v111
	v_cvt_pk_bf16_f32 v224, v115, v119
	v_cvt_pk_bf16_f32 v225, v123, v127
	ds_write2_b64 v1, v[218:219], v[220:221] offset0:17 offset1:18
	ds_write2_b64 v1, v[222:223], v[224:225] offset0:19 offset1:20
	v_cvt_pk_bf16_f32 v218, v68, v72
	v_cvt_pk_bf16_f32 v219, v76, v80
	v_cvt_pk_bf16_f32 v220, v84, v88
	v_cvt_pk_bf16_f32 v221, v92, v96
	v_cvt_pk_bf16_f32 v222, v100, v104
	v_cvt_pk_bf16_f32 v223, v108, v112
	v_cvt_pk_bf16_f32 v224, v116, v120
	v_cvt_pk_bf16_f32 v225, v124, v128
	ds_write_b128 v1, v[218:221] offset:272
	ds_write_b128 v1, v[222:225] offset:288
	v_cvt_pk_bf16_f32 v218, v69, v73
	v_cvt_pk_bf16_f32 v219, v77, v81
	v_cvt_pk_bf16_f32 v220, v85, v89
	v_cvt_pk_bf16_f32 v221, v93, v97
	v_cvt_pk_bf16_f32 v222, v101, v105
	v_cvt_pk_bf16_f32 v223, v109, v113
	v_cvt_pk_bf16_f32 v224, v117, v121
	v_cvt_pk_bf16_f32 v225, v125, v129
	ds_write2_b64 v1, v[218:219], v[220:221] offset0:51 offset1:52
	ds_write2_b64 v1, v[222:223], v[224:225] offset0:53 offset1:54
	s_waitcnt lgkmcnt(0)
	ds_read2_b64 v[218:221], v199 offset1:1
	v_lshl_add_u64 v[226:227], s[8:9], 0, v[202:203]
	v_mad_u64_u32 v[222:223], s[14:15], s40, v198, 0
	v_lshl_add_u64 v[228:229], v[222:223], 1, v[226:227]
	ds_read2_b64 v[222:225], v199 offset0:136 offset1:137
	s_waitcnt lgkmcnt(1)
	global_store_dwordx4 v[228:229], v[218:221], off
	s_andn2_b64 vcc, exec, s[16:17]
	s_nop 0
	v_mad_u64_u32 v[218:219], s[14:15], s40, v204, 0
	v_lshl_add_u64 v[218:219], v[218:219], 1, v[226:227]
	s_waitcnt lgkmcnt(0)
	global_store_dwordx4 v[218:219], v[222:225], off
	ds_read2_b64 v[218:221], v201 offset1:1
	s_nop 0
	v_mad_u64_u32 v[222:223], s[14:15], s40, v206, 0
	v_lshl_add_u64 v[228:229], v[222:223], 1, v[226:227]
	ds_read2_b64 v[222:225], v205 offset1:1
	s_waitcnt lgkmcnt(1)
	global_store_dwordx4 v[228:229], v[218:221], off
	s_nop 1
	v_mad_u64_u32 v[218:219], s[14:15], s40, v208, 0
	v_lshl_add_u64 v[218:219], v[218:219], 1, v[226:227]
	s_waitcnt lgkmcnt(0)
	global_store_dwordx4 v[218:219], v[222:225], off
	ds_read2_b64 v[218:221], v207 offset1:1
	s_nop 0
	v_mad_u64_u32 v[222:223], s[14:15], s40, v210, 0
	v_lshl_add_u64 v[228:229], v[222:223], 1, v[226:227]
	ds_read2_b64 v[222:225], v209 offset1:1
	s_waitcnt lgkmcnt(1)
	global_store_dwordx4 v[228:229], v[218:221], off
	s_nop 1
	v_mad_u64_u32 v[218:219], s[14:15], s40, v212, 0
	v_lshl_add_u64 v[218:219], v[218:219], 1, v[226:227]
	s_waitcnt lgkmcnt(0)
	global_store_dwordx4 v[218:219], v[222:225], off
	ds_read2_b64 v[218:221], v211 offset1:1
	s_nop 0
	v_mad_u64_u32 v[222:223], s[14:15], s40, v214, 0
	v_lshl_add_u64 v[228:229], v[222:223], 1, v[226:227]
	ds_read2_b64 v[222:225], v213 offset1:1
	s_waitcnt lgkmcnt(1)
	global_store_dwordx4 v[228:229], v[218:221], off
	s_nop 1
	v_mad_u64_u32 v[218:219], s[14:15], s40, v216, 0
	v_lshl_add_u64 v[218:219], v[218:219], 1, v[226:227]
	s_waitcnt lgkmcnt(0)
	global_store_dwordx4 v[218:219], v[222:225], off
	s_waitcnt lgkmcnt(0)
	s_cbranch_vccnz .LBB0_425
	v_readlane_b32 s14, v255, 11
	s_add_i32 s43, s42, s14
	v_readlane_b32 s15, v255, 12
	s_cmp_lt_i32 s43, 0x100c0
	s_cselect_b64 s[14:15], -1, 0
	s_cmp_gt_i32 s43, 0x100bf
	s_cbranch_scc1 .LBB0_439
	s_cmpk_gt_u32 s43, 0x3ff
	s_cbranch_scc1 .LBB0_426
	s_mov_b64 s[8:9], s[0:1]
	s_load_dwordx2 s[8:9], s[8:9], 0xa0
	s_lshl_b32 s10, s43, 1
	s_and_b32 s10, s10, 0x7c0
	s_lshl_b32 s16, s10, 13
	s_movk_i32 s47, 0x800
	s_waitcnt lgkmcnt(0)
	s_add_u32 s8, s8, s16
	s_addc_u32 s9, s9, 0
	s_lshl_b32 s16, s43, 6
	s_and_b32 s20, s16, 0x7c0
	s_lshl_b32 s16, s20, 2
	s_add_u32 s16, s8, s16
	s_addc_u32 s17, s9, 0
	s_lshl_b32 s8, s20, 12
	s_add_u32 s8, s25, s8
	s_addc_u32 s9, s26, 0
	s_lshl_b32 s10, s10, 1
	s_add_u32 s8, s8, s10
	s_addc_u32 s9, s9, 0
	s_add_i32 s10, s43, 0xfffffc00
	s_cmpk_gt_u32 s10, 0xfff
	s_cbranch_scc0 .LBB0_427
	s_branch .LBB0_428

.LBB0_445:
	s_and_b64 vcc, exec, s[6:7]
	s_cbranch_vccz .LBB0_712
	v_readlane_b32 s14, v255, 9
	s_cmp_lt_i32 s14, 0x100c0
	v_readlane_b32 s15, v255, 10
	s_cbranch_scc0 .LBB0_449
	s_cmpk_gt_u32 s14, 0x3ff
	s_cbranch_scc1 .LBB0_454
	s_mov_b64 s[6:7], s[0:1]
	s_load_dwordx2 s[6:7], s[6:7], 0xa0
	s_lshl_b32 s3, s14, 1
	s_and_b32 s3, s3, 0x7c0
	s_lshl_b32 s8, s3, 13
	s_movk_i32 s15, 0x800
	s_waitcnt lgkmcnt(0)
	s_add_u32 s6, s6, s8
	s_addc_u32 s7, s7, 0
	s_lshl_b32 s8, s14, 6
	s_and_b32 s10, s8, 0x7c0
	s_lshl_b32 s8, s10, 2
	s_add_u32 s8, s6, s8
	s_addc_u32 s9, s7, 0
	s_lshl_b32 s6, s10, 12
	s_add_u32 s6, s38, s6
	s_addc_u32 s7, s39, 0
	s_lshl_b32 s3, s3, 1
	s_add_u32 s3, s6, s3
	s_addc_u32 s7, s7, 0
	s_add_u32 s6, s3, 0x2c00000
	s_addc_u32 s7, s7, 0
	s_add_i32 s3, s14, 0xfffffc00
	s_cmpk_gt_u32 s3, 0xfff
	s_cbranch_scc0 .LBB0_455
	s_branch .LBB0_456

.LBB0_466:
	v_and_b32_e32 v1, 48, v0
	v_mul_u32_u24_e32 v2, s15, v1
	v_lshlrev_b32_e32 v4, 2, v0
	v_mov_b32_e32 v197, 0
	v_lshlrev_b32_e32 v196, 2, v2
	v_and_b32_e32 v130, 60, v4
	v_lshl_add_u64 v[2:3], s[8:9], 0, v[196:197]
	v_lshlrev_b32_e32 v196, 2, v130
	s_mov_b32 s13, 0
	v_lshl_add_u64 v[10:11], v[2:3], 0, v[196:197]
	s_lshl_b32 s12, s15, 2
	v_lshl_add_u64 v[12:13], v[10:11], 0, s[12:13]
	v_lshl_add_u64 v[18:19], v[12:13], 0, s[12:13]
	v_lshl_add_u64 v[20:21], v[18:19], 0, s[12:13]
	v_lshl_add_u64 v[26:27], v[20:21], 0, s[12:13]
	v_lshl_add_u64 v[28:29], v[26:27], 0, s[12:13]
	v_lshl_add_u64 v[34:35], v[28:29], 0, s[12:13]
	v_lshl_add_u64 v[36:37], v[34:35], 0, s[12:13]
	v_lshl_add_u64 v[38:39], v[36:37], 0, s[12:13]
	v_lshl_add_u64 v[42:43], v[38:39], 0, s[12:13]
	v_lshl_add_u64 v[46:47], v[42:43], 0, s[12:13]
	v_lshl_add_u64 v[50:51], v[46:47], 0, s[12:13]
	v_lshl_add_u64 v[54:55], v[50:51], 0, s[12:13]
	v_lshl_add_u64 v[58:59], v[54:55], 0, s[12:13]
	v_lshl_add_u64 v[62:63], v[58:59], 0, s[12:13]
	global_load_dwordx4 v[2:5], v[10:11], off nt
	global_load_dwordx4 v[6:9], v[12:13], off nt
	s_nop 0
	global_load_dwordx4 v[10:13], v[18:19], off nt
	global_load_dwordx4 v[14:17], v[20:21], off nt
	s_nop 0
	global_load_dwordx4 v[18:21], v[26:27], off nt
	global_load_dwordx4 v[22:25], v[28:29], off nt
	s_nop 0
	global_load_dwordx4 v[26:29], v[34:35], off nt
	global_load_dwordx4 v[30:33], v[36:37], off nt
	v_readlane_b32 s8, v255, 11
	global_load_dwordx4 v[34:37], v[38:39], off nt
	v_readlane_b32 s10, v255, 9
	global_load_dwordx4 v[38:41], v[42:43], off nt
	v_readlane_b32 s9, v255, 12
	global_load_dwordx4 v[42:45], v[46:47], off nt
	s_mov_b32 s40, s23
	global_load_dwordx4 v[46:49], v[50:51], off nt
	v_readlane_b32 s11, v255, 10
	global_load_dwordx4 v[50:53], v[54:55], off nt
	s_nop 0
	global_load_dwordx4 v[54:57], v[58:59], off nt
	s_nop 0
	global_load_dwordx4 v[58:61], v[62:63], off nt
	v_lshl_add_u64 v[62:63], v[62:63], 0, s[12:13]
	global_load_dwordx4 v[62:65], v[62:63], off nt
	s_add_i32 s12, s8, s10
	s_cmp_lt_i32 s12, 0x100c0
	s_cselect_b64 s[14:15], -1, 0
	s_cmp_gt_i32 s12, 0x100bf
	s_mov_b64 s[8:9], s[6:7]
	s_cbranch_scc1 .LBB0_486
	s_mov_b64 s[10:11], 0
	s_cmpk_gt_u32 s12, 0x3ff
	s_mov_b64 s[8:9], 0
	s_cbranch_scc1 .LBB0_475
	s_mov_b64 s[8:9], s[0:1]
	s_load_dwordx2 s[8:9], s[8:9], 0xa0
	s_lshl_b32 s10, s12, 1
	s_and_b32 s13, s10, 0x7c0
	s_lshl_b32 s10, s13, 13
	s_waitcnt lgkmcnt(0)
	s_add_u32 s8, s8, s10
	s_addc_u32 s9, s9, 0
	s_lshl_b32 s10, s12, 6
	s_and_b32 s16, s10, 0x7c0
	s_lshl_b32 s10, s16, 2
	s_add_u32 s10, s8, s10
	s_addc_u32 s11, s9, 0
	s_lshl_b32 s8, s16, 12
	s_add_u32 s8, s38, s8
	s_addc_u32 s9, s39, 0
	s_lshl_b32 s13, s13, 1
	s_add_u32 s8, s8, s13
	s_addc_u32 s9, s9, 0
	s_add_u32 s8, s8, 0x2c00000
	s_addc_u32 s9, s9, 0
	s_movk_i32 s13, 0x800
	s_add_i32 s16, s12, 0xfffffc00
	s_cmpk_gt_u32 s16, 0xfff
	s_cbranch_scc0 .LBB0_476

.LBB0_505:
	s_waitcnt vmcnt(14)
	v_cvt_pk_bf16_f32 v218, v2, v6
	s_waitcnt vmcnt(12)
	v_cvt_pk_bf16_f32 v219, v10, v14
	s_waitcnt vmcnt(10)
	v_cvt_pk_bf16_f32 v220, v18, v22
	s_waitcnt vmcnt(8)
	v_cvt_pk_bf16_f32 v221, v26, v30
	s_waitcnt vmcnt(6)
	v_cvt_pk_bf16_f32 v222, v34, v38
	s_waitcnt vmcnt(4)
	v_cvt_pk_bf16_f32 v223, v42, v46
	s_waitcnt vmcnt(2)
	v_cvt_pk_bf16_f32 v224, v50, v54
	s_waitcnt vmcnt(0)
	v_cvt_pk_bf16_f32 v225, v58, v62
	ds_write_b128 v195, v[218:221]
	ds_write_b128 v195, v[222:225] offset:16
	v_cvt_pk_bf16_f32 v218, v3, v7
	v_cvt_pk_bf16_f32 v219, v11, v15
	v_cvt_pk_bf16_f32 v220, v19, v23
	v_cvt_pk_bf16_f32 v221, v27, v31
	v_cvt_pk_bf16_f32 v222, v35, v39
	v_cvt_pk_bf16_f32 v223, v43, v47
	v_cvt_pk_bf16_f32 v224, v51, v55
	v_cvt_pk_bf16_f32 v225, v59, v63
	ds_write2_b64 v195, v[218:219], v[220:221] offset0:17 offset1:18
	ds_write2_b64 v195, v[222:223], v[224:225] offset0:19 offset1:20
	v_cvt_pk_bf16_f32 v218, v4, v8
	v_cvt_pk_bf16_f32 v219, v12, v16
	v_cvt_pk_bf16_f32 v220, v20, v24
	v_cvt_pk_bf16_f32 v221, v28, v32
	v_cvt_pk_bf16_f32 v222, v36, v40
	v_cvt_pk_bf16_f32 v223, v44, v48
	v_cvt_pk_bf16_f32 v224, v52, v56
	v_cvt_pk_bf16_f32 v225, v60, v64
	ds_write_b128 v195, v[218:221] offset:272
	ds_write_b128 v195, v[222:225] offset:288
	v_cvt_pk_bf16_f32 v218, v5, v9
	v_cvt_pk_bf16_f32 v219, v13, v17
	v_cvt_pk_bf16_f32 v220, v21, v25
	v_cvt_pk_bf16_f32 v221, v29, v33
	v_cvt_pk_bf16_f32 v222, v37, v41
	v_cvt_pk_bf16_f32 v223, v45, v49
	v_cvt_pk_bf16_f32 v224, v53, v57
	v_cvt_pk_bf16_f32 v225, v61, v65
	ds_write2_b64 v195, v[218:219], v[220:221] offset0:51 offset1:52
	ds_write2_b64 v195, v[222:223], v[224:225] offset0:53 offset1:54
	s_waitcnt lgkmcnt(0)
	v_lshlrev_b32_e32 v202, 1, v200
	ds_read2_b64 v[218:221], v199 offset1:1
	v_lshl_add_u64 v[226:227], s[6:7], 0, v[202:203]
	v_mad_u64_u32 v[222:223], s[18:19], s23, v198, 0
	v_lshl_add_u64 v[228:229], v[222:223], 1, v[226:227]
	ds_read2_b64 v[222:225], v199 offset0:136 offset1:137
	s_waitcnt lgkmcnt(1)
	global_store_dwordx4 v[228:229], v[218:221], off
	v_add_u32_e32 v201, 0x880, v199
	v_add_u32_e32 v205, 0xcc0, v199
	v_mad_u64_u32 v[218:219], s[18:19], s23, v204, 0
	v_lshl_add_u64 v[218:219], v[218:219], 1, v[226:227]
	s_waitcnt lgkmcnt(0)
	global_store_dwordx4 v[218:219], v[222:225], off
	ds_read2_b64 v[218:221], v201 offset1:1
	v_add_u32_e32 v207, 0x1100, v199
	v_mad_u64_u32 v[222:223], s[18:19], s23, v206, 0
	v_lshl_add_u64 v[228:229], v[222:223], 1, v[226:227]
	ds_read2_b64 v[222:225], v205 offset1:1
	s_waitcnt lgkmcnt(1)
	global_store_dwordx4 v[228:229], v[218:221], off
	v_add_u32_e32 v209, 0x1540, v199
	v_add_u32_e32 v211, 0x1980, v199
	v_mad_u64_u32 v[218:219], s[18:19], s23, v208, 0
	v_lshl_add_u64 v[218:219], v[218:219], 1, v[226:227]
	s_waitcnt lgkmcnt(0)
	global_store_dwordx4 v[218:219], v[222:225], off
	ds_read2_b64 v[218:221], v207 offset1:1
	v_add_u32_e32 v213, 0x1dc0, v199
	v_mad_u64_u32 v[222:223], s[18:19], s23, v210, 0
	v_lshl_add_u64 v[228:229], v[222:223], 1, v[226:227]
	ds_read2_b64 v[222:225], v209 offset1:1
	s_waitcnt lgkmcnt(1)
	global_store_dwordx4 v[228:229], v[218:221], off
	s_andn2_b64 vcc, exec, s[14:15]
	s_nop 0
	v_mad_u64_u32 v[218:219], s[18:19], s23, v212, 0
	v_lshl_add_u64 v[218:219], v[218:219], 1, v[226:227]
	s_waitcnt lgkmcnt(0)
	global_store_dwordx4 v[218:219], v[222:225], off
	ds_read2_b64 v[218:221], v211 offset1:1
	s_nop 0
	v_mad_u64_u32 v[222:223], s[18:19], s23, v214, 0
	v_lshl_add_u64 v[228:229], v[222:223], 1, v[226:227]
	ds_read2_b64 v[222:225], v213 offset1:1
	s_waitcnt lgkmcnt(1)
	global_store_dwordx4 v[228:229], v[218:221], off
	s_nop 1
	v_mad_u64_u32 v[218:219], s[18:19], s23, v216, 0
	v_lshl_add_u64 v[218:219], v[218:219], 1, v[226:227]
	s_waitcnt lgkmcnt(0)
	global_store_dwordx4 v[218:219], v[222:225], off
	s_waitcnt lgkmcnt(0)
	s_mov_b64 s[18:19], 0
	s_cbranch_vccnz .LBB0_487
	s_add_i32 s42, s35, s34
	s_cmp_gt_i32 s42, 0x100bf
	s_cselect_b64 s[18:19], -1, 0
	s_and_b64 vcc, exec, s[18:19]
	s_cbranch_vccnz .LBB0_526
	s_cmpk_gt_u32 s42, 0x3ff
	s_cbranch_scc1 .LBB0_513
	s_mov_b64 s[6:7], s[0:1]
	s_load_dwordx2 s[6:7], s[6:7], 0xa0
	s_lshl_b32 s10, s42, 1
	s_and_b32 s10, s10, 0x7c0
	s_lshl_b32 s14, s10, 13
	s_movk_i32 s46, 0x800
	s_waitcnt lgkmcnt(0)
	s_add_u32 s6, s6, s14
	s_addc_u32 s7, s7, 0
	s_lshl_b32 s14, s42, 6
	s_and_b32 s20, s14, 0x7c0
	s_lshl_b32 s14, s20, 2
	s_add_u32 s14, s6, s14
	s_addc_u32 s15, s7, 0
	s_lshl_b32 s6, s20, 12
	s_add_u32 s6, s25, s6
	s_addc_u32 s7, s26, 0
	s_lshl_b32 s10, s10, 1
	s_add_u32 s6, s6, s10
	s_addc_u32 s7, s7, 0
	s_add_i32 s10, s42, 0xfffffc00
	s_cmpk_gt_u32 s10, 0xfff
	s_cbranch_scc0 .LBB0_514
	s_branch .LBB0_515

.LBB0_526:
	v_cvt_pk_bf16_f32 v218, v66, v70
	v_cvt_pk_bf16_f32 v219, v74, v78
	v_cvt_pk_bf16_f32 v220, v82, v86
	v_cvt_pk_bf16_f32 v221, v90, v94
	v_cvt_pk_bf16_f32 v222, v98, v102
	v_cvt_pk_bf16_f32 v223, v106, v110
	v_cvt_pk_bf16_f32 v224, v114, v118
	v_cvt_pk_bf16_f32 v225, v122, v126
	ds_write_b128 v195, v[218:221]
	ds_write_b128 v195, v[222:225] offset:16
	v_cvt_pk_bf16_f32 v218, v67, v71
	v_cvt_pk_bf16_f32 v219, v75, v79
	v_cvt_pk_bf16_f32 v220, v83, v87
	v_cvt_pk_bf16_f32 v221, v91, v95
	v_cvt_pk_bf16_f32 v222, v99, v103
	v_cvt_pk_bf16_f32 v223, v107, v111
	v_cvt_pk_bf16_f32 v224, v115, v119
	v_cvt_pk_bf16_f32 v225, v123, v127
	ds_write2_b64 v195, v[218:219], v[220:221] offset0:17 offset1:18
	ds_write2_b64 v195, v[222:223], v[224:225] offset0:19 offset1:20
	v_cvt_pk_bf16_f32 v218, v68, v72
	v_cvt_pk_bf16_f32 v219, v76, v80
	v_cvt_pk_bf16_f32 v220, v84, v88
	v_cvt_pk_bf16_f32 v221, v92, v96
	v_cvt_pk_bf16_f32 v222, v100, v104
	v_cvt_pk_bf16_f32 v223, v108, v112
	v_cvt_pk_bf16_f32 v224, v116, v120
	v_cvt_pk_bf16_f32 v225, v124, v128
	ds_write_b128 v195, v[218:221] offset:272
	ds_write_b128 v195, v[222:225] offset:288
	v_cvt_pk_bf16_f32 v218, v69, v73
	v_cvt_pk_bf16_f32 v219, v77, v81
	v_cvt_pk_bf16_f32 v220, v85, v89
	v_cvt_pk_bf16_f32 v221, v93, v97
	v_cvt_pk_bf16_f32 v222, v101, v105
	v_cvt_pk_bf16_f32 v223, v109, v113
	v_cvt_pk_bf16_f32 v224, v117, v121
	v_cvt_pk_bf16_f32 v225, v125, v129
	ds_write2_b64 v195, v[218:219], v[220:221] offset0:51 offset1:52
	ds_write2_b64 v195, v[222:223], v[224:225] offset0:53 offset1:54
	s_waitcnt lgkmcnt(0)
	ds_read2_b64 v[218:221], v199 offset1:1
	v_lshl_add_u64 v[226:227], s[8:9], 0, v[202:203]
	v_mad_u64_u32 v[222:223], s[14:15], s40, v198, 0
	v_lshl_add_u64 v[228:229], v[222:223], 1, v[226:227]
	ds_read2_b64 v[222:225], v199 offset0:136 offset1:137
	s_waitcnt lgkmcnt(1)
	global_store_dwordx4 v[228:229], v[218:221], off
	s_andn2_b64 vcc, exec, s[16:17]
	s_nop 0
	v_mad_u64_u32 v[218:219], s[14:15], s40, v204, 0
	v_lshl_add_u64 v[218:219], v[218:219], 1, v[226:227]
	s_waitcnt lgkmcnt(0)
	global_store_dwordx4 v[218:219], v[222:225], off
	ds_read2_b64 v[218:221], v201 offset1:1
	s_nop 0
	v_mad_u64_u32 v[222:223], s[14:15], s40, v206, 0
	v_lshl_add_u64 v[228:229], v[222:223], 1, v[226:227]
	ds_read2_b64 v[222:225], v205 offset1:1
	s_waitcnt lgkmcnt(1)
	global_store_dwordx4 v[228:229], v[218:221], off
	s_nop 1
	v_mad_u64_u32 v[218:219], s[14:15], s40, v208, 0
	v_lshl_add_u64 v[218:219], v[218:219], 1, v[226:227]
	s_waitcnt lgkmcnt(0)
	global_store_dwordx4 v[218:219], v[222:225], off
	ds_read2_b64 v[218:221], v207 offset1:1
	s_nop 0
	v_mad_u64_u32 v[222:223], s[14:15], s40, v210, 0
	v_lshl_add_u64 v[228:229], v[222:223], 1, v[226:227]
	ds_read2_b64 v[222:225], v209 offset1:1
	s_waitcnt lgkmcnt(1)
	global_store_dwordx4 v[228:229], v[218:221], off
	s_nop 1
	v_mad_u64_u32 v[218:219], s[14:15], s40, v212, 0
	v_lshl_add_u64 v[218:219], v[218:219], 1, v[226:227]
	s_waitcnt lgkmcnt(0)
	global_store_dwordx4 v[218:219], v[222:225], off
	ds_read2_b64 v[218:221], v211 offset1:1
	s_nop 0
	v_mad_u64_u32 v[222:223], s[14:15], s40, v214, 0
	v_lshl_add_u64 v[228:229], v[222:223], 1, v[226:227]
	ds_read2_b64 v[222:225], v213 offset1:1
	s_waitcnt lgkmcnt(1)
	global_store_dwordx4 v[228:229], v[218:221], off
	s_nop 1
	v_mad_u64_u32 v[218:219], s[14:15], s40, v216, 0
	v_lshl_add_u64 v[218:219], v[218:219], 1, v[226:227]
	s_waitcnt lgkmcnt(0)
	global_store_dwordx4 v[218:219], v[222:225], off
	s_waitcnt lgkmcnt(0)
	s_cbranch_vccnz .LBB0_534
	v_readlane_b32 s14, v255, 11
	s_add_i32 s43, s42, s14
	v_readlane_b32 s15, v255, 12
	s_cmp_lt_i32 s43, 0x100c0
	s_cselect_b64 s[14:15], -1, 0
	s_cmp_gt_i32 s43, 0x100bf
	s_cbranch_scc1 .LBB0_548
	s_cmpk_gt_u32 s43, 0x3ff
	s_cbranch_scc1 .LBB0_535
	s_mov_b64 s[8:9], s[0:1]
	s_load_dwordx2 s[8:9], s[8:9], 0xa0
	s_lshl_b32 s10, s43, 1
	s_and_b32 s10, s10, 0x7c0
	s_lshl_b32 s16, s10, 13
	s_movk_i32 s47, 0x800
	s_waitcnt lgkmcnt(0)
	s_add_u32 s8, s8, s16
	s_addc_u32 s9, s9, 0
	s_lshl_b32 s16, s43, 6
	s_and_b32 s20, s16, 0x7c0
	s_lshl_b32 s16, s20, 2
	s_add_u32 s16, s8, s16
	s_addc_u32 s17, s9, 0
	s_lshl_b32 s8, s20, 12
	s_add_u32 s8, s25, s8
	s_addc_u32 s9, s26, 0
	s_lshl_b32 s10, s10, 1
	s_add_u32 s8, s8, s10
	s_addc_u32 s9, s9, 0
	s_add_i32 s10, s43, 0xfffffc00
	s_cmpk_gt_u32 s10, 0xfff
	s_cbranch_scc0 .LBB0_536
	s_branch .LBB0_537

.LBB0_974:
	v_readfirstlane_b32 s3, v0
	s_nop 3
	s_lshr_b32 s3, s3, 6
	s_lshl_b32 s6, s2, 3
	s_add_i32 s6, s6, s3
	s_lshl_b32 s7, s44, 3
	s_cmpk_lg_i32 s44, 0x100
	s_cbranch_scc1 .Ldc_go
	s_cmp_lt_u32 s2, 8
	s_cbranch_scc1 .Ldc_done
	s_addk_i32 s6, 0xffc0
	s_movk_i32 s7, 0x7c0
.Ldc_go:
	s_add_i32 s6, s6, 0x13c0
	s_cmpk_gt_u32 s6, 0x2aff
	s_cbranch_scc1 .Ldc_done
	s_load_dwordx2 s[20:21], s[0:1], 0x100
	v_mbcnt_lo_u32_b32 v1, -1, 0
	v_mbcnt_hi_u32_b32 v1, -1, v1
	v_lshrrev_b32_e32 v2, 4, v1
	v_and_b32_e32 v3, 15, v1
	v_mul_u32_u24_e32 v200, 0xac000, v2
	v_lshl_add_u32 v200, v3, 4, v200
	s_lshl_b32 s8, s3, 14
	v_mul_u32_u24_e32 v201, 0x220, v3
	v_lshl_add_u32 v201, v2, 5, v201
	v_add_u32_e32 v201, s8, v201
	v_lshrrev_b32_e32 v2, 3, v1
	v_and_b32_e32 v3, 7, v1
	v_mul_u32_u24_e32 v202, 0x88, v2
	v_lshl_add_u32 v202, v3, 4, v202
	v_add_u32_e32 v202, s8, v202
	v_lshlrev_b32_e32 v203, 13, v2
	v_lshl_add_u32 v203, v3, 4, v203
	s_add_u32 s22, s38, 0x21600000
	s_addc_u32 s23, s39, 0
	s_waitcnt lgkmcnt(0)
	s_add_u32 s20, s20, 0xac00000
	s_addc_u32 s21, s21, 0
	s_mul_hi_u32 s10, s6, 0x17d05f5
	s_mul_i32 s8, s10, 0xac
	s_sub_i32 s11, s6, s8
	s_mul_i32 s8, s10, 0x2b0000
	s_lshl_b32 s9, s11, 8
	s_add_i32 s8, s8, s9
	s_add_u32 s14, s20, s8
	s_addc_u32 s15, s21, 0
	global_load_dwordx4 v[2:5], v200, s[14:15] nt
	s_add_u32 s14, s14, 0xac00
	s_addc_u32 s15, s15, 0
	global_load_dwordx4 v[6:9], v200, s[14:15] nt
	s_add_u32 s14, s14, 0xac00
	s_addc_u32 s15, s15, 0
	global_load_dwordx4 v[10:13], v200, s[14:15] nt
	s_add_u32 s14, s14, 0xac00
	s_addc_u32 s15, s15, 0
	global_load_dwordx4 v[14:17], v200, s[14:15] nt
	s_add_u32 s14, s14, 0xac00
	s_addc_u32 s15, s15, 0
	global_load_dwordx4 v[18:21], v200, s[14:15] nt
	s_add_u32 s14, s14, 0xac00
	s_addc_u32 s15, s15, 0
	global_load_dwordx4 v[22:25], v200, s[14:15] nt
	s_add_u32 s14, s14, 0xac00
	s_addc_u32 s15, s15, 0
	global_load_dwordx4 v[26:29], v200, s[14:15] nt
	s_add_u32 s14, s14, 0xac00
	s_addc_u32 s15, s15, 0
	global_load_dwordx4 v[30:33], v200, s[14:15] nt
	s_add_u32 s14, s14, 0xac00
	s_addc_u32 s15, s15, 0
	global_load_dwordx4 v[34:37], v200, s[14:15] nt
	s_add_u32 s14, s14, 0xac00
	s_addc_u32 s15, s15, 0
	global_load_dwordx4 v[38:41], v200, s[14:15] nt
	s_add_u32 s14, s14, 0xac00
	s_addc_u32 s15, s15, 0
	global_load_dwordx4 v[42:45], v200, s[14:15] nt
	s_add_u32 s14, s14, 0xac00
	s_addc_u32 s15, s15, 0
	global_load_dwordx4 v[46:49], v200, s[14:15] nt
	s_add_u32 s14, s14, 0xac00
	s_addc_u32 s15, s15, 0
	global_load_dwordx4 v[50:53], v200, s[14:15] nt
	s_add_u32 s14, s14, 0xac00
	s_addc_u32 s15, s15, 0
	global_load_dwordx4 v[54:57], v200, s[14:15] nt
	s_add_u32 s14, s14, 0xac00
	s_addc_u32 s15, s15, 0
	global_load_dwordx4 v[58:61], v200, s[14:15] nt
	s_add_u32 s14, s14, 0xac00
	s_addc_u32 s15, s15, 0
	global_load_dwordx4 v[62:65], v200, s[14:15] nt
.Ldc_loop:
	s_add_i32 s24, s6, s7
	s_cmpk_gt_u32 s24, 0x2aff
	s_cbranch_scc1 .Ldc_lastA
	s_mul_hi_u32 s10, s24, 0x17d05f5
	s_mul_i32 s8, s10, 0xac
	s_sub_i32 s11, s24, s8
	s_mul_i32 s8, s10, 0x2b0000
	s_lshl_b32 s9, s11, 8
	s_add_i32 s8, s8, s9
	s_add_u32 s14, s20, s8
	s_addc_u32 s15, s21, 0
	global_load_dwordx4 v[66:69], v200, s[14:15] nt
	s_add_u32 s14, s14, 0xac00
	s_addc_u32 s15, s15, 0
	global_load_dwordx4 v[70:73], v200, s[14:15] nt
	s_add_u32 s14, s14, 0xac00
	s_addc_u32 s15, s15, 0
	global_load_dwordx4 v[74:77], v200, s[14:15] nt
	s_add_u32 s14, s14, 0xac00
	s_addc_u32 s15, s15, 0
	global_load_dwordx4 v[78:81], v200, s[14:15] nt
	s_add_u32 s14, s14, 0xac00
	s_addc_u32 s15, s15, 0
	global_load_dwordx4 v[82:85], v200, s[14:15] nt
	s_add_u32 s14, s14, 0xac00
	s_addc_u32 s15, s15, 0
	global_load_dwordx4 v[86:89], v200, s[14:15] nt
	s_add_u32 s14, s14, 0xac00
	s_addc_u32 s15, s15, 0
	global_load_dwordx4 v[90:93], v200, s[14:15] nt
	s_add_u32 s14, s14, 0xac00
	s_addc_u32 s15, s15, 0
	global_load_dwordx4 v[94:97], v200, s[14:15] nt
	s_add_u32 s14, s14, 0xac00
	s_addc_u32 s15, s15, 0
	global_load_dwordx4 v[98:101], v200, s[14:15] nt
	s_add_u32 s14, s14, 0xac00
	s_addc_u32 s15, s15, 0
	global_load_dwordx4 v[102:105], v200, s[14:15] nt
	s_add_u32 s14, s14, 0xac00
	s_addc_u32 s15, s15, 0
	global_load_dwordx4 v[106:109], v200, s[14:15] nt
	s_add_u32 s14, s14, 0xac00
	s_addc_u32 s15, s15, 0
	global_load_dwordx4 v[110:113], v200, s[14:15] nt
	s_add_u32 s14, s14, 0xac00
	s_addc_u32 s15, s15, 0
	global_load_dwordx4 v[114:117], v200, s[14:15] nt
	s_add_u32 s14, s14, 0xac00
	s_addc_u32 s15, s15, 0
	global_load_dwordx4 v[118:121], v200, s[14:15] nt
	s_add_u32 s14, s14, 0xac00
	s_addc_u32 s15, s15, 0
	global_load_dwordx4 v[122:125], v200, s[14:15] nt
	s_add_u32 s14, s14, 0xac00
	s_addc_u32 s15, s15, 0
	global_load_dwordx4 v[126:129], v200, s[14:15] nt
	s_waitcnt vmcnt(16)
	s_mul_hi_u32 s10, s6, 0x17d05f5
	s_mul_i32 s8, s10, 0xac
	s_sub_i32 s11, s6, s8
	s_lshr_b32 s8, s11, 1
	s_lshl_b32 s8, s8, 8
	s_and_b32 s9, s11, 1
	s_lshl_b32 s9, s9, 6
	s_add_i32 s8, s8, s9
	s_addk_i32 s8, 0x80
	s_lshl_b32 s8, s8, 13
	s_lshl_b32 s9, s10, 7
	s_add_i32 s8, s8, s9
	s_add_u32 s18, s22, s8
	s_addc_u32 s19, s23, 0
	v_cvt_pk_bf16_f32 v130, v2, v6
	v_cvt_pk_bf16_f32 v131, v10, v14
	v_cvt_pk_bf16_f32 v132, v18, v22
	v_cvt_pk_bf16_f32 v133, v26, v30
	v_cvt_pk_bf16_f32 v134, v34, v38
	v_cvt_pk_bf16_f32 v135, v42, v46
	v_cvt_pk_bf16_f32 v136, v50, v54
	v_cvt_pk_bf16_f32 v137, v58, v62
	v_cvt_pk_bf16_f32 v138, v3, v7
	v_cvt_pk_bf16_f32 v139, v11, v15
	v_cvt_pk_bf16_f32 v140, v19, v23
	v_cvt_pk_bf16_f32 v141, v27, v31
	v_cvt_pk_bf16_f32 v142, v35, v39
	v_cvt_pk_bf16_f32 v143, v43, v47
	v_cvt_pk_bf16_f32 v144, v51, v55
	v_cvt_pk_bf16_f32 v145, v59, v63
	v_cvt_pk_bf16_f32 v146, v4, v8
	v_cvt_pk_bf16_f32 v147, v12, v16
	v_cvt_pk_bf16_f32 v148, v20, v24
	v_cvt_pk_bf16_f32 v149, v28, v32
	v_cvt_pk_bf16_f32 v150, v36, v40
	v_cvt_pk_bf16_f32 v151, v44, v48
	v_cvt_pk_bf16_f32 v152, v52, v56
	v_cvt_pk_bf16_f32 v153, v60, v64
	v_cvt_pk_bf16_f32 v154, v5, v9
	v_cvt_pk_bf16_f32 v155, v13, v17
	v_cvt_pk_bf16_f32 v156, v21, v25
	v_cvt_pk_bf16_f32 v157, v29, v33
	v_cvt_pk_bf16_f32 v158, v37, v41
	v_cvt_pk_bf16_f32 v159, v45, v49
	v_cvt_pk_bf16_f32 v160, v53, v57
	v_cvt_pk_bf16_f32 v161, v61, v65
	ds_write_b64 v201, v[130:131]
	ds_write_b64 v201, v[132:133] offset:8
	ds_write_b64 v201, v[134:135] offset:16
	ds_write_b64 v201, v[136:137] offset:24
	ds_write_b64 v201, v[138:139] offset:136
	ds_write_b64 v201, v[140:141] offset:144
	ds_write_b64 v201, v[142:143] offset:152
	ds_write_b64 v201, v[144:145] offset:160
	ds_write_b64 v201, v[146:147] offset:272
	ds_write_b64 v201, v[148:149] offset:280
	ds_write_b64 v201, v[150:151] offset:288
	ds_write_b64 v201, v[152:153] offset:296
	ds_write_b64 v201, v[154:155] offset:408
	ds_write_b64 v201, v[156:157] offset:416
	ds_write_b64 v201, v[158:159] offset:424
	ds_write_b64 v201, v[160:161] offset:432
	s_waitcnt lgkmcnt(0)
	ds_read_b64 v[162:163], v202
	ds_read_b64 v[164:165], v202 offset:8
	ds_read_b64 v[166:167], v202 offset:1088
	ds_read_b64 v[168:169], v202 offset:1096
	ds_read_b64 v[170:171], v202 offset:2176
	ds_read_b64 v[172:173], v202 offset:2184
	ds_read_b64 v[174:175], v202 offset:3264
	ds_read_b64 v[176:177], v202 offset:3272
	ds_read_b64 v[178:179], v202 offset:4352
	ds_read_b64 v[180:181], v202 offset:4360
	ds_read_b64 v[182:183], v202 offset:5440
	ds_read_b64 v[184:185], v202 offset:5448
	ds_read_b64 v[186:187], v202 offset:6528
	ds_read_b64 v[188:189], v202 offset:6536
	ds_read_b64 v[190:191], v202 offset:7616
	ds_read_b64 v[192:193], v202 offset:7624
	s_waitcnt lgkmcnt(14)
	global_store_dwordx4 v203, v[162:165], s[18:19]
	s_add_u32 s18, s18, 0x10000
	s_addc_u32 s19, s19, 0
	s_waitcnt lgkmcnt(12)
	global_store_dwordx4 v203, v[166:169], s[18:19]
	s_add_u32 s18, s18, 0x10000
	s_addc_u32 s19, s19, 0
	s_waitcnt lgkmcnt(10)
	global_store_dwordx4 v203, v[170:173], s[18:19]
	s_add_u32 s18, s18, 0x10000
	s_addc_u32 s19, s19, 0
	s_waitcnt lgkmcnt(8)
	global_store_dwordx4 v203, v[174:177], s[18:19]
	s_add_u32 s18, s18, 0x10000
	s_addc_u32 s19, s19, 0
	s_waitcnt lgkmcnt(6)
	global_store_dwordx4 v203, v[178:181], s[18:19]
	s_add_u32 s18, s18, 0x10000
	s_addc_u32 s19, s19, 0
	s_waitcnt lgkmcnt(4)
	global_store_dwordx4 v203, v[182:185], s[18:19]
	s_add_u32 s18, s18, 0x10000
	s_addc_u32 s19, s19, 0
	s_waitcnt lgkmcnt(2)
	global_store_dwordx4 v203, v[186:189], s[18:19]
	s_add_u32 s18, s18, 0x10000
	s_addc_u32 s19, s19, 0
	s_waitcnt lgkmcnt(0)
	global_store_dwordx4 v203, v[190:193], s[18:19]
	s_mov_b32 s6, s24
	s_add_i32 s24, s6, s7
	s_cmpk_gt_u32 s24, 0x2aff
	s_cbranch_scc1 .Ldc_lastB
	s_mul_hi_u32 s10, s24, 0x17d05f5
	s_mul_i32 s8, s10, 0xac
	s_sub_i32 s11, s24, s8
	s_mul_i32 s8, s10, 0x2b0000
	s_lshl_b32 s9, s11, 8
	s_add_i32 s8, s8, s9
	s_add_u32 s14, s20, s8
	s_addc_u32 s15, s21, 0
	global_load_dwordx4 v[2:5], v200, s[14:15] nt
	s_add_u32 s14, s14, 0xac00
	s_addc_u32 s15, s15, 0
	global_load_dwordx4 v[6:9], v200, s[14:15] nt
	s_add_u32 s14, s14, 0xac00
	s_addc_u32 s15, s15, 0
	global_load_dwordx4 v[10:13], v200, s[14:15] nt
	s_add_u32 s14, s14, 0xac00
	s_addc_u32 s15, s15, 0
	global_load_dwordx4 v[14:17], v200, s[14:15] nt
	s_add_u32 s14, s14, 0xac00
	s_addc_u32 s15, s15, 0
	global_load_dwordx4 v[18:21], v200, s[14:15] nt
	s_add_u32 s14, s14, 0xac00
	s_addc_u32 s15, s15, 0
	global_load_dwordx4 v[22:25], v200, s[14:15] nt
	s_add_u32 s14, s14, 0xac00
	s_addc_u32 s15, s15, 0
	global_load_dwordx4 v[26:29], v200, s[14:15] nt
	s_add_u32 s14, s14, 0xac00
	s_addc_u32 s15, s15, 0
	global_load_dwordx4 v[30:33], v200, s[14:15] nt
	s_add_u32 s14, s14, 0xac00
	s_addc_u32 s15, s15, 0
	global_load_dwordx4 v[34:37], v200, s[14:15] nt
	s_add_u32 s14, s14, 0xac00
	s_addc_u32 s15, s15, 0
	global_load_dwordx4 v[38:41], v200, s[14:15] nt
	s_add_u32 s14, s14, 0xac00
	s_addc_u32 s15, s15, 0
	global_load_dwordx4 v[42:45], v200, s[14:15] nt
	s_add_u32 s14, s14, 0xac00
	s_addc_u32 s15, s15, 0
	global_load_dwordx4 v[46:49], v200, s[14:15] nt
	s_add_u32 s14, s14, 0xac00
	s_addc_u32 s15, s15, 0
	global_load_dwordx4 v[50:53], v200, s[14:15] nt
	s_add_u32 s14, s14, 0xac00
	s_addc_u32 s15, s15, 0
	global_load_dwordx4 v[54:57], v200, s[14:15] nt
	s_add_u32 s14, s14, 0xac00
	s_addc_u32 s15, s15, 0
	global_load_dwordx4 v[58:61], v200, s[14:15] nt
	s_add_u32 s14, s14, 0xac00
	s_addc_u32 s15, s15, 0
	global_load_dwordx4 v[62:65], v200, s[14:15] nt
	s_waitcnt vmcnt(16)
	s_mul_hi_u32 s10, s6, 0x17d05f5
	s_mul_i32 s8, s10, 0xac
	s_sub_i32 s11, s6, s8
	s_lshr_b32 s8, s11, 1
	s_lshl_b32 s8, s8, 8
	s_and_b32 s9, s11, 1
	s_lshl_b32 s9, s9, 6
	s_add_i32 s8, s8, s9
	s_addk_i32 s8, 0x80
	s_lshl_b32 s8, s8, 13
	s_lshl_b32 s9, s10, 7
	s_add_i32 s8, s8, s9
	s_add_u32 s18, s22, s8
	s_addc_u32 s19, s23, 0
	v_cvt_pk_bf16_f32 v130, v66, v70
	v_cvt_pk_bf16_f32 v131, v74, v78
	v_cvt_pk_bf16_f32 v132, v82, v86
	v_cvt_pk_bf16_f32 v133, v90, v94
	v_cvt_pk_bf16_f32 v134, v98, v102
	v_cvt_pk_bf16_f32 v135, v106, v110
	v_cvt_pk_bf16_f32 v136, v114, v118
	v_cvt_pk_bf16_f32 v137, v122, v126
	v_cvt_pk_bf16_f32 v138, v67, v71
	v_cvt_pk_bf16_f32 v139, v75, v79
	v_cvt_pk_bf16_f32 v140, v83, v87
	v_cvt_pk_bf16_f32 v141, v91, v95
	v_cvt_pk_bf16_f32 v142, v99, v103
	v_cvt_pk_bf16_f32 v143, v107, v111
	v_cvt_pk_bf16_f32 v144, v115, v119
	v_cvt_pk_bf16_f32 v145, v123, v127
	v_cvt_pk_bf16_f32 v146, v68, v72
	v_cvt_pk_bf16_f32 v147, v76, v80
	v_cvt_pk_bf16_f32 v148, v84, v88
	v_cvt_pk_bf16_f32 v149, v92, v96
	v_cvt_pk_bf16_f32 v150, v100, v104
	v_cvt_pk_bf16_f32 v151, v108, v112
	v_cvt_pk_bf16_f32 v152, v116, v120
	v_cvt_pk_bf16_f32 v153, v124, v128
	v_cvt_pk_bf16_f32 v154, v69, v73
	v_cvt_pk_bf16_f32 v155, v77, v81
	v_cvt_pk_bf16_f32 v156, v85, v89
	v_cvt_pk_bf16_f32 v157, v93, v97
	v_cvt_pk_bf16_f32 v158, v101, v105
	v_cvt_pk_bf16_f32 v159, v109, v113
	v_cvt_pk_bf16_f32 v160, v117, v121
	v_cvt_pk_bf16_f32 v161, v125, v129
	ds_write_b64 v201, v[130:131]
	ds_write_b64 v201, v[132:133] offset:8
	ds_write_b64 v201, v[134:135] offset:16
	ds_write_b64 v201, v[136:137] offset:24
	ds_write_b64 v201, v[138:139] offset:136
	ds_write_b64 v201, v[140:141] offset:144
	ds_write_b64 v201, v[142:143] offset:152
	ds_write_b64 v201, v[144:145] offset:160
	ds_write_b64 v201, v[146:147] offset:272
	ds_write_b64 v201, v[148:149] offset:280
	ds_write_b64 v201, v[150:151] offset:288
	ds_write_b64 v201, v[152:153] offset:296
	ds_write_b64 v201, v[154:155] offset:408
	ds_write_b64 v201, v[156:157] offset:416
	ds_write_b64 v201, v[158:159] offset:424
	ds_write_b64 v201, v[160:161] offset:432
	s_waitcnt lgkmcnt(0)
	ds_read_b64 v[162:163], v202
	ds_read_b64 v[164:165], v202 offset:8
	ds_read_b64 v[166:167], v202 offset:1088
	ds_read_b64 v[168:169], v202 offset:1096
	ds_read_b64 v[170:171], v202 offset:2176
	ds_read_b64 v[172:173], v202 offset:2184
	ds_read_b64 v[174:175], v202 offset:3264
	ds_read_b64 v[176:177], v202 offset:3272
	ds_read_b64 v[178:179], v202 offset:4352
	ds_read_b64 v[180:181], v202 offset:4360
	ds_read_b64 v[182:183], v202 offset:5440
	ds_read_b64 v[184:185], v202 offset:5448
	ds_read_b64 v[186:187], v202 offset:6528
	ds_read_b64 v[188:189], v202 offset:6536
	ds_read_b64 v[190:191], v202 offset:7616
	ds_read_b64 v[192:193], v202 offset:7624
	s_waitcnt lgkmcnt(14)
	global_store_dwordx4 v203, v[162:165], s[18:19]
	s_add_u32 s18, s18, 0x10000
	s_addc_u32 s19, s19, 0
	s_waitcnt lgkmcnt(12)
	global_store_dwordx4 v203, v[166:169], s[18:19]
	s_add_u32 s18, s18, 0x10000
	s_addc_u32 s19, s19, 0
	s_waitcnt lgkmcnt(10)
	global_store_dwordx4 v203, v[170:173], s[18:19]
	s_add_u32 s18, s18, 0x10000
	s_addc_u32 s19, s19, 0
	s_waitcnt lgkmcnt(8)
	global_store_dwordx4 v203, v[174:177], s[18:19]
	s_add_u32 s18, s18, 0x10000
	s_addc_u32 s19, s19, 0
	s_waitcnt lgkmcnt(6)
	global_store_dwordx4 v203, v[178:181], s[18:19]
	s_add_u32 s18, s18, 0x10000
	s_addc_u32 s19, s19, 0
	s_waitcnt lgkmcnt(4)
	global_store_dwordx4 v203, v[182:185], s[18:19]
	s_add_u32 s18, s18, 0x10000
	s_addc_u32 s19, s19, 0
	s_waitcnt lgkmcnt(2)
	global_store_dwordx4 v203, v[186:189], s[18:19]
	s_add_u32 s18, s18, 0x10000
	s_addc_u32 s19, s19, 0
	s_waitcnt lgkmcnt(0)
	global_store_dwordx4 v203, v[190:193], s[18:19]
	s_mov_b32 s6, s24
	s_branch .Ldc_loop
.Ldc_lastA:
	s_waitcnt vmcnt(0)
	s_mul_hi_u32 s10, s6, 0x17d05f5
	s_mul_i32 s8, s10, 0xac
	s_sub_i32 s11, s6, s8
	s_lshr_b32 s8, s11, 1
	s_lshl_b32 s8, s8, 8
	s_and_b32 s9, s11, 1
	s_lshl_b32 s9, s9, 6
	s_add_i32 s8, s8, s9
	s_addk_i32 s8, 0x80
	s_lshl_b32 s8, s8, 13
	s_lshl_b32 s9, s10, 7
	s_add_i32 s8, s8, s9
	s_add_u32 s18, s22, s8
	s_addc_u32 s19, s23, 0
	v_cvt_pk_bf16_f32 v130, v2, v6
	v_cvt_pk_bf16_f32 v131, v10, v14
	v_cvt_pk_bf16_f32 v132, v18, v22
	v_cvt_pk_bf16_f32 v133, v26, v30
	v_cvt_pk_bf16_f32 v134, v34, v38
	v_cvt_pk_bf16_f32 v135, v42, v46
	v_cvt_pk_bf16_f32 v136, v50, v54
	v_cvt_pk_bf16_f32 v137, v58, v62
	v_cvt_pk_bf16_f32 v138, v3, v7
	v_cvt_pk_bf16_f32 v139, v11, v15
	v_cvt_pk_bf16_f32 v140, v19, v23
	v_cvt_pk_bf16_f32 v141, v27, v31
	v_cvt_pk_bf16_f32 v142, v35, v39
	v_cvt_pk_bf16_f32 v143, v43, v47
	v_cvt_pk_bf16_f32 v144, v51, v55
	v_cvt_pk_bf16_f32 v145, v59, v63
	v_cvt_pk_bf16_f32 v146, v4, v8
	v_cvt_pk_bf16_f32 v147, v12, v16
	v_cvt_pk_bf16_f32 v148, v20, v24
	v_cvt_pk_bf16_f32 v149, v28, v32
	v_cvt_pk_bf16_f32 v150, v36, v40
	v_cvt_pk_bf16_f32 v151, v44, v48
	v_cvt_pk_bf16_f32 v152, v52, v56
	v_cvt_pk_bf16_f32 v153, v60, v64
	v_cvt_pk_bf16_f32 v154, v5, v9
	v_cvt_pk_bf16_f32 v155, v13, v17
	v_cvt_pk_bf16_f32 v156, v21, v25
	v_cvt_pk_bf16_f32 v157, v29, v33
	v_cvt_pk_bf16_f32 v158, v37, v41
	v_cvt_pk_bf16_f32 v159, v45, v49
	v_cvt_pk_bf16_f32 v160, v53, v57
	v_cvt_pk_bf16_f32 v161, v61, v65
	ds_write_b64 v201, v[130:131]
	ds_write_b64 v201, v[132:133] offset:8
	ds_write_b64 v201, v[134:135] offset:16
	ds_write_b64 v201, v[136:137] offset:24
	ds_write_b64 v201, v[138:139] offset:136
	ds_write_b64 v201, v[140:141] offset:144
	ds_write_b64 v201, v[142:143] offset:152
	ds_write_b64 v201, v[144:145] offset:160
	ds_write_b64 v201, v[146:147] offset:272
	ds_write_b64 v201, v[148:149] offset:280
	ds_write_b64 v201, v[150:151] offset:288
	ds_write_b64 v201, v[152:153] offset:296
	ds_write_b64 v201, v[154:155] offset:408
	ds_write_b64 v201, v[156:157] offset:416
	ds_write_b64 v201, v[158:159] offset:424
	ds_write_b64 v201, v[160:161] offset:432
	s_waitcnt lgkmcnt(0)
	ds_read_b64 v[162:163], v202
	ds_read_b64 v[164:165], v202 offset:8
	ds_read_b64 v[166:167], v202 offset:1088
	ds_read_b64 v[168:169], v202 offset:1096
	ds_read_b64 v[170:171], v202 offset:2176
	ds_read_b64 v[172:173], v202 offset:2184
	ds_read_b64 v[174:175], v202 offset:3264
	ds_read_b64 v[176:177], v202 offset:3272
	ds_read_b64 v[178:179], v202 offset:4352
	ds_read_b64 v[180:181], v202 offset:4360
	ds_read_b64 v[182:183], v202 offset:5440
	ds_read_b64 v[184:185], v202 offset:5448
	ds_read_b64 v[186:187], v202 offset:6528
	ds_read_b64 v[188:189], v202 offset:6536
	ds_read_b64 v[190:191], v202 offset:7616
	ds_read_b64 v[192:193], v202 offset:7624
	s_waitcnt lgkmcnt(14)
	global_store_dwordx4 v203, v[162:165], s[18:19]
	s_add_u32 s18, s18, 0x10000
	s_addc_u32 s19, s19, 0
	s_waitcnt lgkmcnt(12)
	global_store_dwordx4 v203, v[166:169], s[18:19]
	s_add_u32 s18, s18, 0x10000
	s_addc_u32 s19, s19, 0
	s_waitcnt lgkmcnt(10)
	global_store_dwordx4 v203, v[170:173], s[18:19]
	s_add_u32 s18, s18, 0x10000
	s_addc_u32 s19, s19, 0
	s_waitcnt lgkmcnt(8)
	global_store_dwordx4 v203, v[174:177], s[18:19]
	s_add_u32 s18, s18, 0x10000
	s_addc_u32 s19, s19, 0
	s_waitcnt lgkmcnt(6)
	global_store_dwordx4 v203, v[178:181], s[18:19]
	s_add_u32 s18, s18, 0x10000
	s_addc_u32 s19, s19, 0
	s_waitcnt lgkmcnt(4)
	global_store_dwordx4 v203, v[182:185], s[18:19]
	s_add_u32 s18, s18, 0x10000
	s_addc_u32 s19, s19, 0
	s_waitcnt lgkmcnt(2)
	global_store_dwordx4 v203, v[186:189], s[18:19]
	s_add_u32 s18, s18, 0x10000
	s_addc_u32 s19, s19, 0
	s_waitcnt lgkmcnt(0)
	global_store_dwordx4 v203, v[190:193], s[18:19]
	s_branch .Ldc_done
.Ldc_lastB:
	s_waitcnt vmcnt(0)
	s_mul_hi_u32 s10, s6, 0x17d05f5
	s_mul_i32 s8, s10, 0xac
	s_sub_i32 s11, s6, s8
	s_lshr_b32 s8, s11, 1
	s_lshl_b32 s8, s8, 8
	s_and_b32 s9, s11, 1
	s_lshl_b32 s9, s9, 6
	s_add_i32 s8, s8, s9
	s_addk_i32 s8, 0x80
	s_lshl_b32 s8, s8, 13
	s_lshl_b32 s9, s10, 7
	s_add_i32 s8, s8, s9
	s_add_u32 s18, s22, s8
	s_addc_u32 s19, s23, 0
	v_cvt_pk_bf16_f32 v130, v66, v70
	v_cvt_pk_bf16_f32 v131, v74, v78
	v_cvt_pk_bf16_f32 v132, v82, v86
	v_cvt_pk_bf16_f32 v133, v90, v94
	v_cvt_pk_bf16_f32 v134, v98, v102
	v_cvt_pk_bf16_f32 v135, v106, v110
	v_cvt_pk_bf16_f32 v136, v114, v118
	v_cvt_pk_bf16_f32 v137, v122, v126
	v_cvt_pk_bf16_f32 v138, v67, v71
	v_cvt_pk_bf16_f32 v139, v75, v79
	v_cvt_pk_bf16_f32 v140, v83, v87
	v_cvt_pk_bf16_f32 v141, v91, v95
	v_cvt_pk_bf16_f32 v142, v99, v103
	v_cvt_pk_bf16_f32 v143, v107, v111
	v_cvt_pk_bf16_f32 v144, v115, v119
	v_cvt_pk_bf16_f32 v145, v123, v127
	v_cvt_pk_bf16_f32 v146, v68, v72
	v_cvt_pk_bf16_f32 v147, v76, v80
	v_cvt_pk_bf16_f32 v148, v84, v88
	v_cvt_pk_bf16_f32 v149, v92, v96
	v_cvt_pk_bf16_f32 v150, v100, v104
	v_cvt_pk_bf16_f32 v151, v108, v112
	v_cvt_pk_bf16_f32 v152, v116, v120
	v_cvt_pk_bf16_f32 v153, v124, v128
	v_cvt_pk_bf16_f32 v154, v69, v73
	v_cvt_pk_bf16_f32 v155, v77, v81
	v_cvt_pk_bf16_f32 v156, v85, v89
	v_cvt_pk_bf16_f32 v157, v93, v97
	v_cvt_pk_bf16_f32 v158, v101, v105
	v_cvt_pk_bf16_f32 v159, v109, v113
	v_cvt_pk_bf16_f32 v160, v117, v121
	v_cvt_pk_bf16_f32 v161, v125, v129
	ds_write_b64 v201, v[130:131]
	ds_write_b64 v201, v[132:133] offset:8
	ds_write_b64 v201, v[134:135] offset:16
	ds_write_b64 v201, v[136:137] offset:24
	ds_write_b64 v201, v[138:139] offset:136
	ds_write_b64 v201, v[140:141] offset:144
	ds_write_b64 v201, v[142:143] offset:152
	ds_write_b64 v201, v[144:145] offset:160
	ds_write_b64 v201, v[146:147] offset:272
	ds_write_b64 v201, v[148:149] offset:280
	ds_write_b64 v201, v[150:151] offset:288
	ds_write_b64 v201, v[152:153] offset:296
	ds_write_b64 v201, v[154:155] offset:408
	ds_write_b64 v201, v[156:157] offset:416
	ds_write_b64 v201, v[158:159] offset:424
	ds_write_b64 v201, v[160:161] offset:432
	s_waitcnt lgkmcnt(0)
	ds_read_b64 v[162:163], v202
	ds_read_b64 v[164:165], v202 offset:8
	ds_read_b64 v[166:167], v202 offset:1088
	ds_read_b64 v[168:169], v202 offset:1096
	ds_read_b64 v[170:171], v202 offset:2176
	ds_read_b64 v[172:173], v202 offset:2184
	ds_read_b64 v[174:175], v202 offset:3264
	ds_read_b64 v[176:177], v202 offset:3272
	ds_read_b64 v[178:179], v202 offset:4352
	ds_read_b64 v[180:181], v202 offset:4360
	ds_read_b64 v[182:183], v202 offset:5440
	ds_read_b64 v[184:185], v202 offset:5448
	ds_read_b64 v[186:187], v202 offset:6528
	ds_read_b64 v[188:189], v202 offset:6536
	ds_read_b64 v[190:191], v202 offset:7616
	ds_read_b64 v[192:193], v202 offset:7624
	s_waitcnt lgkmcnt(14)
	global_store_dwordx4 v203, v[162:165], s[18:19]
	s_add_u32 s18, s18, 0x10000
	s_addc_u32 s19, s19, 0
	s_waitcnt lgkmcnt(12)
	global_store_dwordx4 v203, v[166:169], s[18:19]
	s_add_u32 s18, s18, 0x10000
	s_addc_u32 s19, s19, 0
	s_waitcnt lgkmcnt(10)
	global_store_dwordx4 v203, v[170:173], s[18:19]
	s_add_u32 s18, s18, 0x10000
	s_addc_u32 s19, s19, 0
	s_waitcnt lgkmcnt(8)
	global_store_dwordx4 v203, v[174:177], s[18:19]
	s_add_u32 s18, s18, 0x10000
	s_addc_u32 s19, s19, 0
	s_waitcnt lgkmcnt(6)
	global_store_dwordx4 v203, v[178:181], s[18:19]
	s_add_u32 s18, s18, 0x10000
	s_addc_u32 s19, s19, 0
	s_waitcnt lgkmcnt(4)
	global_store_dwordx4 v203, v[182:185], s[18:19]
	s_add_u32 s18, s18, 0x10000
	s_addc_u32 s19, s19, 0
	s_waitcnt lgkmcnt(2)
	global_store_dwordx4 v203, v[186:189], s[18:19]
	s_add_u32 s18, s18, 0x10000
	s_addc_u32 s19, s19, 0
	s_waitcnt lgkmcnt(0)
	global_store_dwordx4 v203, v[190:193], s[18:19]
